# PEER table conversion: the 8 row loads issued together with one wait (3 serialized instances), plus hyena load de-serialization and conv-loop rewrite
# speedup vs baseline: 1.0207x; 1.0126x over previous
.LBB0_749:
	s_add_i32 s21, s20, s51
	s_cmpk_lt_i32 s21, 0x4000
	s_cselect_b64 s[26:27], -1, 0
	s_add_i32 s28, s21, 0xffffc000
	s_cmpk_gt_i32 s21, 0x3fff
	s_cselect_b64 s[0:1], -1, 0
	s_and_b64 s[10:11], s[0:1], exec
	s_cselect_b32 s11, s94, s92
	s_cselect_b32 s28, s28, s21
	s_cselect_b32 s10, s95, s93
	s_add_u32 s30, s11, s22
	s_addc_u32 s31, s10, s23
	s_ashr_i32 s29, s28, 31
	s_lshl_b64 s[10:11], s[28:29], 13
	s_add_u32 s10, s30, s10
	s_addc_u32 s11, s31, s11
	global_load_dwordx4 v[2:5], v34, s[10:11]
	v_lshl_add_u64 v[18:19], s[10:11], 0, v[34:35]
	v_add_co_u32_e32 v30, vcc, s40, v18
	v_mov_b32_e32 v74, 1.0
	s_nop 0
	v_addc_co_u32_e32 v31, vcc, 0, v19, vcc
	global_load_dwordx4 v[6:9], v34, s[10:11] offset:1024
	global_load_dwordx4 v[10:13], v34, s[10:11] offset:2048
	global_load_dwordx4 v[14:17], v34, s[10:11] offset:3072
	global_load_dwordx4 v[18:21], v[30:31], off
	global_load_dwordx4 v[22:25], v[30:31], off offset:1024
	global_load_dwordx4 v[26:29], v[30:31], off offset:2048
	s_nop 0
	global_load_dwordx4 v[30:33], v[30:31], off offset:3072
	s_waitcnt vmcnt(0)
	v_max3_f32 v36, |v2|, |v3|, |v4|
	v_max3_f32 v36, v36, |v5|, |v6|
	v_max3_f32 v36, v36, |v7|, |v8|
	v_max3_f32 v36, v36, |v9|, |v10|
	v_max3_f32 v36, v36, |v11|, |v12|
	v_max3_f32 v36, v36, |v13|, |v14|
	v_max3_f32 v36, v36, |v15|, |v16|
	v_max3_f32 v36, v36, |v17|, |v18|
	v_max3_f32 v36, v36, |v19|, |v20|
	v_max3_f32 v36, v36, |v21|, |v22|
	v_max3_f32 v36, v36, |v23|, |v24|
	v_max3_f32 v36, v36, |v25|, |v26|
	v_max3_f32 v36, v36, |v27|, |v28|
	v_max3_f32 v36, v36, |v29|, |v30|
	v_max3_f32 v36, v36, |v31|, |v32|
	v_max_f32_e64 v36, v36, |v33|
	ds_bpermute_b32 v37, v51, v36
	s_waitcnt lgkmcnt(0)
	v_max_f32_e32 v37, v37, v37
	v_max_f32_e32 v36, v36, v37
	ds_bpermute_b32 v37, v52, v36
	s_waitcnt lgkmcnt(0)
	v_max_f32_e32 v37, v37, v37
	v_max_f32_e32 v36, v36, v37
	ds_bpermute_b32 v37, v53, v36
	s_waitcnt lgkmcnt(0)
	v_max_f32_e32 v37, v37, v37
	v_max_f32_e32 v36, v36, v37
	ds_bpermute_b32 v37, v54, v36
	s_waitcnt lgkmcnt(0)
	v_max_f32_e32 v37, v37, v37
	v_max_f32_e32 v36, v36, v37
	ds_bpermute_b32 v37, v55, v36
	s_waitcnt lgkmcnt(0)
	v_max_f32_e32 v37, v37, v37
	v_max_f32_e32 v36, v36, v37
	ds_bpermute_b32 v37, v56, v36
	s_waitcnt lgkmcnt(0)
	v_max_f32_e32 v37, v37, v37
	v_max_f32_e32 v57, v36, v37
	v_cmp_lt_f32_e64 s[10:11], 0, v57
	s_and_saveexec_b64 s[30:31], s[10:11]
	s_cbranch_execz .LBB0_751
	v_cndmask_b32_e64 v36, v47, v48, s[0:1]
	v_div_scale_f32 v37, s[52:53], v57, v57, v36
	v_rcp_f32_e32 v58, v37
	v_div_scale_f32 v59, vcc, v36, v57, v36
	v_fma_f32 v60, -v37, v58, 1.0
	v_fmac_f32_e32 v58, v60, v58
	v_mul_f32_e32 v60, v59, v58
	v_fma_f32 v61, -v37, v60, v59
	v_fmac_f32_e32 v60, v61, v58
	v_fma_f32 v37, -v37, v60, v59
	v_div_fmas_f32 v37, v37, v58, v60
	v_div_fixup_f32 v74, v37, v57, v36

.LBB0_757:
	s_or_b64 exec, exec, s[26:27]
	s_add_i32 s28, s21, 1
	s_cmpk_lt_i32 s28, 0x4000
	s_cselect_b64 s[26:27], -1, 0
	s_addk_i32 s21, 0xc001
	s_cmpk_gt_i32 s28, 0x3fff
	s_cselect_b64 s[0:1], -1, 0
	s_and_b64 s[10:11], s[0:1], exec
	s_cselect_b32 s11, s94, s92
	s_cselect_b32 s28, s21, s28
	s_cselect_b32 s10, s95, s93
	s_add_u32 s21, s11, s22
	s_addc_u32 s30, s10, s23
	s_ashr_i32 s29, s28, 31
	s_lshl_b64 s[10:11], s[28:29], 13
	s_add_u32 s10, s21, s10
	s_addc_u32 s11, s30, s11
	global_load_dwordx4 v[2:5], v34, s[10:11]
	v_lshl_add_u64 v[18:19], s[10:11], 0, v[34:35]
	v_add_co_u32_e32 v30, vcc, s40, v18
	v_mov_b32_e32 v74, 1.0
	s_nop 0
	v_addc_co_u32_e32 v31, vcc, 0, v19, vcc
	global_load_dwordx4 v[6:9], v34, s[10:11] offset:1024
	global_load_dwordx4 v[10:13], v34, s[10:11] offset:2048
	global_load_dwordx4 v[14:17], v34, s[10:11] offset:3072
	global_load_dwordx4 v[18:21], v[30:31], off
	global_load_dwordx4 v[22:25], v[30:31], off offset:1024
	global_load_dwordx4 v[26:29], v[30:31], off offset:2048
	s_nop 0
	global_load_dwordx4 v[30:33], v[30:31], off offset:3072
	s_waitcnt vmcnt(0)
	v_max3_f32 v36, |v2|, |v3|, |v4|
	v_max3_f32 v36, v36, |v5|, |v6|
	v_max3_f32 v36, v36, |v7|, |v8|
	v_max3_f32 v36, v36, |v9|, |v10|
	v_max3_f32 v36, v36, |v11|, |v12|
	v_max3_f32 v36, v36, |v13|, |v14|
	v_max3_f32 v36, v36, |v15|, |v16|
	v_max3_f32 v36, v36, |v17|, |v18|
	v_max3_f32 v36, v36, |v19|, |v20|
	v_max3_f32 v36, v36, |v21|, |v22|
	v_max3_f32 v36, v36, |v23|, |v24|
	v_max3_f32 v36, v36, |v25|, |v26|
	v_max3_f32 v36, v36, |v27|, |v28|
	v_max3_f32 v36, v36, |v29|, |v30|
	v_max3_f32 v36, v36, |v31|, |v32|
	v_max_f32_e64 v36, v36, |v33|
	ds_bpermute_b32 v37, v51, v36
	s_waitcnt lgkmcnt(0)
	v_max_f32_e32 v37, v37, v37
	v_max_f32_e32 v36, v36, v37
	ds_bpermute_b32 v37, v52, v36
	s_waitcnt lgkmcnt(0)
	v_max_f32_e32 v37, v37, v37
	v_max_f32_e32 v36, v36, v37
	ds_bpermute_b32 v37, v53, v36
	s_waitcnt lgkmcnt(0)
	v_max_f32_e32 v37, v37, v37
	v_max_f32_e32 v36, v36, v37
	ds_bpermute_b32 v37, v54, v36
	s_waitcnt lgkmcnt(0)
	v_max_f32_e32 v37, v37, v37
	v_max_f32_e32 v36, v36, v37
	ds_bpermute_b32 v37, v55, v36
	s_waitcnt lgkmcnt(0)
	v_max_f32_e32 v37, v37, v37
	v_max_f32_e32 v36, v36, v37
	ds_bpermute_b32 v37, v56, v36
	s_waitcnt lgkmcnt(0)
	v_max_f32_e32 v37, v37, v37
	v_max_f32_e32 v57, v36, v37
	v_cmp_lt_f32_e64 s[10:11], 0, v57
	s_and_saveexec_b64 s[30:31], s[10:11]
	s_cbranch_execz .LBB0_759
	v_cndmask_b32_e64 v36, v47, v48, s[0:1]
	v_div_scale_f32 v37, s[52:53], v57, v57, v36
	v_rcp_f32_e32 v58, v37
	v_div_scale_f32 v59, vcc, v36, v57, v36
	v_fma_f32 v60, -v37, v58, 1.0
	v_fmac_f32_e32 v58, v60, v58
	v_mul_f32_e32 v60, v59, v58
	v_fma_f32 v61, -v37, v60, v59
	v_fmac_f32_e32 v60, v61, v58
	v_fma_f32 v37, -v37, v60, v59
	v_div_fmas_f32 v37, v37, v58, v60
	v_div_fixup_f32 v74, v37, v57, v36

.LBB0_1788:
	s_add_i32 s21, s20, s55
	s_cmpk_lt_i32 s21, 0x4000
	s_cselect_b64 s[26:27], -1, 0
	s_add_i32 s28, s21, 0xffffc000
	s_cmpk_gt_i32 s21, 0x3fff
	s_cselect_b64 s[0:1], -1, 0
	s_and_b64 s[10:11], s[0:1], exec
	s_cselect_b32 s11, s94, s92
	s_cselect_b32 s28, s28, s21
	s_cselect_b32 s10, s95, s93
	s_add_u32 s30, s11, s22
	s_addc_u32 s31, s10, s23
	s_ashr_i32 s29, s28, 31
	s_lshl_b64 s[10:11], s[28:29], 13
	s_add_u32 s10, s30, s10
	s_addc_u32 s11, s31, s11
	global_load_dwordx4 v[2:5], v34, s[10:11]
	v_lshl_add_u64 v[18:19], s[10:11], 0, v[34:35]
	v_add_co_u32_e32 v30, vcc, s40, v18
	v_mov_b32_e32 v75, 1.0
	s_nop 0
	v_addc_co_u32_e32 v31, vcc, 0, v19, vcc
	global_load_dwordx4 v[6:9], v34, s[10:11] offset:1024
	global_load_dwordx4 v[10:13], v34, s[10:11] offset:2048
	global_load_dwordx4 v[14:17], v34, s[10:11] offset:3072
	global_load_dwordx4 v[18:21], v[30:31], off
	global_load_dwordx4 v[22:25], v[30:31], off offset:1024
	global_load_dwordx4 v[26:29], v[30:31], off offset:2048
	s_nop 0
	global_load_dwordx4 v[30:33], v[30:31], off offset:3072
	s_waitcnt vmcnt(0)
	v_max3_f32 v36, |v2|, |v3|, |v4|
	v_max3_f32 v36, v36, |v5|, |v6|
	v_max3_f32 v36, v36, |v7|, |v8|
	v_max3_f32 v36, v36, |v9|, |v10|
	v_max3_f32 v36, v36, |v11|, |v12|
	v_max3_f32 v36, v36, |v13|, |v14|
	v_max3_f32 v36, v36, |v15|, |v16|
	v_max3_f32 v36, v36, |v17|, |v18|
	v_max3_f32 v36, v36, |v19|, |v20|
	v_max3_f32 v36, v36, |v21|, |v22|
	v_max3_f32 v36, v36, |v23|, |v24|
	v_max3_f32 v36, v36, |v25|, |v26|
	v_max3_f32 v36, v36, |v27|, |v28|
	v_max3_f32 v36, v36, |v29|, |v30|
	v_max3_f32 v36, v36, |v31|, |v32|
	v_max_f32_e64 v36, v36, |v33|
	ds_bpermute_b32 v37, v52, v36
	s_waitcnt lgkmcnt(0)
	v_max_f32_e32 v37, v37, v37
	v_max_f32_e32 v36, v36, v37
	ds_bpermute_b32 v37, v53, v36
	s_waitcnt lgkmcnt(0)
	v_max_f32_e32 v37, v37, v37
	v_max_f32_e32 v36, v36, v37
	ds_bpermute_b32 v37, v54, v36
	s_waitcnt lgkmcnt(0)
	v_max_f32_e32 v37, v37, v37
	v_max_f32_e32 v36, v36, v37
	ds_bpermute_b32 v37, v55, v36
	s_waitcnt lgkmcnt(0)
	v_max_f32_e32 v37, v37, v37
	v_max_f32_e32 v36, v36, v37
	ds_bpermute_b32 v37, v56, v36
	s_waitcnt lgkmcnt(0)
	v_max_f32_e32 v37, v37, v37
	v_max_f32_e32 v36, v36, v37
	ds_bpermute_b32 v37, v57, v36
	s_waitcnt lgkmcnt(0)
	v_max_f32_e32 v37, v37, v37
	v_max_f32_e32 v58, v36, v37
	v_cmp_lt_f32_e64 s[10:11], 0, v58
	s_and_saveexec_b64 s[30:31], s[10:11]
	s_cbranch_execz .LBB0_1790
	v_cndmask_b32_e64 v36, v48, v49, s[0:1]
	v_div_scale_f32 v37, s[56:57], v58, v58, v36
	v_rcp_f32_e32 v59, v37
	v_div_scale_f32 v60, vcc, v36, v58, v36
	v_fma_f32 v61, -v37, v59, 1.0
	v_fmac_f32_e32 v59, v61, v59
	v_mul_f32_e32 v61, v60, v59
	v_fma_f32 v62, -v37, v61, v60
	v_fmac_f32_e32 v61, v62, v59
	v_fma_f32 v37, -v37, v61, v60
	v_div_fmas_f32 v37, v37, v59, v61
	v_div_fixup_f32 v75, v37, v58, v36

.LBB0_1796:
	s_or_b64 exec, exec, s[26:27]
	s_add_i32 s28, s21, 1
	s_cmpk_lt_i32 s28, 0x4000
	s_cselect_b64 s[26:27], -1, 0
	s_addk_i32 s21, 0xc001
	s_cmpk_gt_i32 s28, 0x3fff
	s_cselect_b64 s[0:1], -1, 0
	s_and_b64 s[10:11], s[0:1], exec
	s_cselect_b32 s11, s94, s92
	s_cselect_b32 s28, s21, s28
	s_cselect_b32 s10, s95, s93
	s_add_u32 s21, s11, s22
	s_addc_u32 s30, s10, s23
	s_ashr_i32 s29, s28, 31
	s_lshl_b64 s[10:11], s[28:29], 13
	s_add_u32 s10, s21, s10
	s_addc_u32 s11, s30, s11
	global_load_dwordx4 v[2:5], v34, s[10:11]
	v_lshl_add_u64 v[18:19], s[10:11], 0, v[34:35]
	v_add_co_u32_e32 v30, vcc, s40, v18
	v_mov_b32_e32 v75, 1.0
	s_nop 0
	v_addc_co_u32_e32 v31, vcc, 0, v19, vcc
	global_load_dwordx4 v[6:9], v34, s[10:11] offset:1024
	global_load_dwordx4 v[10:13], v34, s[10:11] offset:2048
	global_load_dwordx4 v[14:17], v34, s[10:11] offset:3072
	global_load_dwordx4 v[18:21], v[30:31], off
	global_load_dwordx4 v[22:25], v[30:31], off offset:1024
	global_load_dwordx4 v[26:29], v[30:31], off offset:2048
	s_nop 0
	global_load_dwordx4 v[30:33], v[30:31], off offset:3072
	s_waitcnt vmcnt(0)
	v_max3_f32 v36, |v2|, |v3|, |v4|
	v_max3_f32 v36, v36, |v5|, |v6|
	v_max3_f32 v36, v36, |v7|, |v8|
	v_max3_f32 v36, v36, |v9|, |v10|
	v_max3_f32 v36, v36, |v11|, |v12|
	v_max3_f32 v36, v36, |v13|, |v14|
	v_max3_f32 v36, v36, |v15|, |v16|
	v_max3_f32 v36, v36, |v17|, |v18|
	v_max3_f32 v36, v36, |v19|, |v20|
	v_max3_f32 v36, v36, |v21|, |v22|
	v_max3_f32 v36, v36, |v23|, |v24|
	v_max3_f32 v36, v36, |v25|, |v26|
	v_max3_f32 v36, v36, |v27|, |v28|
	v_max3_f32 v36, v36, |v29|, |v30|
	v_max3_f32 v36, v36, |v31|, |v32|
	v_max_f32_e64 v36, v36, |v33|
	ds_bpermute_b32 v37, v52, v36
	s_waitcnt lgkmcnt(0)
	v_max_f32_e32 v37, v37, v37
	v_max_f32_e32 v36, v36, v37
	ds_bpermute_b32 v37, v53, v36
	s_waitcnt lgkmcnt(0)
	v_max_f32_e32 v37, v37, v37
	v_max_f32_e32 v36, v36, v37
	ds_bpermute_b32 v37, v54, v36
	s_waitcnt lgkmcnt(0)
	v_max_f32_e32 v37, v37, v37
	v_max_f32_e32 v36, v36, v37
	ds_bpermute_b32 v37, v55, v36
	s_waitcnt lgkmcnt(0)
	v_max_f32_e32 v37, v37, v37
	v_max_f32_e32 v36, v36, v37
	ds_bpermute_b32 v37, v56, v36
	s_waitcnt lgkmcnt(0)
	v_max_f32_e32 v37, v37, v37
	v_max_f32_e32 v36, v36, v37
	ds_bpermute_b32 v37, v57, v36
	s_waitcnt lgkmcnt(0)
	v_max_f32_e32 v37, v37, v37
	v_max_f32_e32 v58, v36, v37
	v_cmp_lt_f32_e64 s[10:11], 0, v58
	s_and_saveexec_b64 s[30:31], s[10:11]
	s_cbranch_execz .LBB0_1798
	v_cndmask_b32_e64 v36, v48, v49, s[0:1]
	v_div_scale_f32 v37, s[56:57], v58, v58, v36
	v_rcp_f32_e32 v59, v37
	v_div_scale_f32 v60, vcc, v36, v58, v36
	v_fma_f32 v61, -v37, v59, 1.0
	v_fmac_f32_e32 v59, v61, v59
	v_mul_f32_e32 v61, v60, v59
	v_fma_f32 v62, -v37, v61, v60
	v_fmac_f32_e32 v61, v62, v59
	v_fma_f32 v37, -v37, v61, v60
	v_div_fmas_f32 v37, v37, v59, v61
	v_div_fixup_f32 v75, v37, v58, v36
